# final row-statistics exchange (P11): its acquire invalidate also issued before the wait
# speedup vs baseline: 1.0041x; 1.0009x over previous
.LBB0_2060:
	s_or_b64 exec, exec, s[10:11]
	s_mov_b32 s3, 0x400001
	buffer_inv sc1
	v_mov_b32_e32 v0, 0
	s_branch .LBB0_2062

.LBB0_2068:
.LBB0_2069:
	s_or_b64 exec, exec, s[0:1]
	s_ashr_i32 s5, s4, 31
	s_lshl_b64 s[0:1], s[4:5], 2
	s_add_u32 s4, s8, s0
	s_addc_u32 s5, s9, s1
	s_ashr_i32 s3, s2, 31
	s_lshl_b64 s[0:1], s[2:3], 2
	v_lshlrev_b64 v[80:81], 2, v[160:161]
	s_add_u32 s6, s4, s0
	v_lshl_add_u64 v[4:5], s[68:69], 0, v[80:81]
	s_addc_u32 s7, s5, s1
	v_lshlrev_b32_e32 v172, 2, v172
	s_barrier
	global_load_dwordx4 v[8:11], v[4:5], off offset:16
	global_load_dwordx4 v[12:15], v[4:5], off
	global_load_dwordx4 v[0:3], v[4:5], off offset:528
	s_nop 0
	global_load_dwordx4 v[4:7], v[4:5], off offset:512
	s_nop 0
	global_load_dword v87, v172, s[6:7] sc1
	global_load_dword v86, v172, s[6:7] offset:64 sc1
	global_load_dword v161, v172, s[6:7] offset:128 sc1
	global_load_dword v160, v172, s[6:7] offset:192 sc1
	v_lshlrev_b64 v[84:85], 12, v[156:157]
	v_lshl_add_u64 v[84:85], s[70:71], 0, v[84:85]
	v_lshlrev_b64 v[82:83], 12, v[158:159]
	v_lshl_add_u64 v[158:159], v[84:85], 0, v[80:81]
	global_load_dword v171, v172, s[6:7] offset:512 sc1
	global_load_dword v170, v172, s[6:7] offset:576 sc1
	global_load_dword v85, v172, s[6:7] offset:640 sc1
	s_mov_b32 s0, 0x358637bd
	s_mov_b32 s4, 0x3a800000
	s_mov_b32 s5, 0x800000
	v_lshl_add_u64 v[156:157], s[70:71], 0, v[82:83]
	v_mov_b64_e32 v[82:83], s[0:1]
	v_lshlrev_b64 v[154:155], 12, v[154:155]
	v_lshl_add_u64 v[156:157], v[156:157], 0, v[80:81]
	v_lshl_add_u64 v[154:155], s[70:71], 0, v[154:155]
	v_lshl_add_u64 v[154:155], v[154:155], 0, v[80:81]
	s_waitcnt vmcnt(5)
	v_pk_fma_f32 v[86:87], v[86:87], s[4:5], v[82:83] op_sel_hi:[1,0,0]
	s_nop 0
	v_mul_f32_e32 v84, 0x4b800000, v87
	s_waitcnt vmcnt(3)
	v_pk_fma_f32 v[160:161], v[160:161], s[4:5], v[82:83] op_sel_hi:[1,0,0]
	v_cmp_gt_f32_e32 vcc, s5, v87
	v_mul_f32_e32 v174, 0x4b800000, v161
	v_cmp_gt_f32_e64 s[2:3], s5, v161
	v_cndmask_b32_e32 v84, v87, v84, vcc
	v_mul_f32_e32 v173, 0x4b800000, v86
	v_cndmask_b32_e64 v87, v161, v174, s[2:3]
	v_rsq_f32_e32 v161, v84
	global_load_dword v84, v172, s[6:7] offset:704 sc1
	v_cmp_gt_f32_e64 s[0:1], s5, v86
	v_rsq_f32_e32 v87, v87
	s_nop 0
	v_cndmask_b32_e64 v86, v86, v173, s[0:1]
	v_rsq_f32_e32 v173, v86
	v_mul_f32_e32 v86, 0x45800000, v161
	v_cndmask_b32_e32 v86, v161, v86, vcc
	v_mul_f32_e32 v174, 0x45800000, v87
	v_mul_f32_e32 v172, 0x45800000, v173
	v_cndmask_b32_e64 v172, v173, v172, s[0:1]
	v_pk_mul_f32 v[124:125], v[124:125], v[86:87] op_sel_hi:[1,0]
	v_pk_mul_f32 v[126:127], v[126:127], v[86:87] op_sel_hi:[1,0]
	v_cndmask_b32_e64 v174, v87, v174, s[2:3]
	v_pk_mul_f32 v[120:121], v[120:121], v[86:87] op_sel_hi:[1,0]
	v_pk_mul_f32 v[122:123], v[122:123], v[86:87] op_sel_hi:[1,0]
	v_pk_mul_f32 v[116:117], v[116:117], v[86:87] op_sel_hi:[1,0]
	v_pk_mul_f32 v[118:119], v[118:119], v[86:87] op_sel_hi:[1,0]
	v_pk_mul_f32 v[112:113], v[112:113], v[86:87] op_sel_hi:[1,0]
	v_pk_mul_f32 v[86:87], v[114:115], v[86:87] op_sel_hi:[1,0]
	v_pk_mul_f32 v[176:177], v[108:109], v[172:173] op_sel_hi:[1,0]
	v_pk_mul_f32 v[114:115], v[110:111], v[172:173] op_sel_hi:[1,0]
	v_pk_mul_f32 v[178:179], v[104:105], v[172:173] op_sel_hi:[1,0]
	v_pk_mul_f32 v[180:181], v[106:107], v[172:173] op_sel_hi:[1,0]
	v_pk_mul_f32 v[182:183], v[100:101], v[172:173] op_sel_hi:[1,0]
	v_pk_mul_f32 v[184:185], v[102:103], v[172:173] op_sel_hi:[1,0]
	v_pk_mul_f32 v[186:187], v[92:93], v[172:173] op_sel_hi:[1,0]
	v_pk_mul_f32 v[172:173], v[94:95], v[172:173] op_sel_hi:[1,0]
	v_pk_mul_f32 v[94:95], v[14:15], v[126:127]
	v_pk_mul_f32 v[92:93], v[12:13], v[124:125]
	v_pk_mul_f32 v[102:103], v[10:11], v[122:123]
	v_pk_mul_f32 v[100:101], v[8:9], v[120:121]
	v_pk_mul_f32 v[106:107], v[6:7], v[118:119]
	v_pk_mul_f32 v[104:105], v[4:5], v[116:117]
	v_pk_mul_f32 v[110:111], v[2:3], v[86:87]
	v_pk_mul_f32 v[108:109], v[0:1], v[112:113]
	v_pk_mul_f32 v[114:115], v[14:15], v[114:115]
	v_pk_mul_f32 v[112:113], v[12:13], v[176:177]
	v_pk_mul_f32 v[118:119], v[10:11], v[180:181]
	v_pk_mul_f32 v[116:117], v[8:9], v[178:179]
	v_pk_mul_f32 v[122:123], v[6:7], v[184:185]
	v_pk_mul_f32 v[120:121], v[4:5], v[182:183]
	v_pk_mul_f32 v[126:127], v[2:3], v[172:173]
	v_pk_mul_f32 v[124:125], v[0:1], v[186:187]
	global_store_dwordx4 v[156:157], v[92:95], off
	global_store_dwordx4 v[156:157], v[100:103], off offset:16
	global_store_dwordx4 v[156:157], v[104:107], off offset:512
	global_store_dwordx4 v[156:157], v[108:111], off offset:528
	global_store_dwordx4 v[158:159], v[112:115], off
	global_store_dwordx4 v[158:159], v[116:119], off offset:16
	global_store_dwordx4 v[158:159], v[120:123], off offset:512
	global_store_dwordx4 v[158:159], v[124:127], off offset:528
	v_pk_mul_f32 v[86:87], v[140:141], v[174:175] op_sel_hi:[1,0]
	v_pk_mul_f32 v[92:93], v[98:99], v[174:175] op_sel_hi:[1,0]
	v_cmp_gt_f32_e32 vcc, s5, v160
	v_pk_mul_f32 v[94:95], v[14:15], v[92:93]
	v_pk_mul_f32 v[92:93], v[12:13], v[86:87]
	global_store_dwordx4 v[154:155], v[92:95], off
	v_pk_mul_f32 v[86:87], v[142:143], v[174:175] op_sel_hi:[1,0]
	s_nop 0
	v_pk_mul_f32 v[92:93], v[96:97], v[174:175] op_sel_hi:[1,0]
	s_nop 0
	v_pk_mul_f32 v[94:95], v[10:11], v[92:93]
	v_pk_mul_f32 v[92:93], v[8:9], v[86:87]
	global_store_dwordx4 v[154:155], v[92:95], off offset:16
	v_pk_mul_f32 v[86:87], v[144:145], v[174:175] op_sel_hi:[1,0]
	s_nop 0
	v_pk_mul_f32 v[92:93], v[136:137], v[174:175] op_sel_hi:[1,0]
	s_nop 0
	v_pk_mul_f32 v[94:95], v[6:7], v[92:93]
	v_pk_mul_f32 v[92:93], v[4:5], v[86:87]
	global_store_dwordx4 v[154:155], v[92:95], off offset:512
	v_pk_mul_f32 v[86:87], v[146:147], v[174:175] op_sel_hi:[1,0]
	s_nop 0
	v_mul_f32_e32 v94, 0x4b800000, v160
	v_cndmask_b32_e32 v94, v160, v94, vcc
	v_rsq_f32_e32 v96, v94
	v_pk_mul_f32 v[92:93], v[138:139], v[174:175] op_sel_hi:[1,0]
	s_nop 0
	v_pk_mul_f32 v[94:95], v[2:3], v[92:93]
	v_pk_mul_f32 v[92:93], v[0:1], v[86:87]
	v_mul_f32_e32 v86, 0x45800000, v96
	v_cndmask_b32_e32 v86, v96, v86, vcc
	v_lshlrev_b64 v[96:97], 12, v[152:153]
	global_store_dwordx4 v[154:155], v[92:95], off offset:528
	v_lshl_add_u64 v[96:97], s[70:71], 0, v[96:97]
	v_lshl_add_u64 v[96:97], v[96:97], 0, v[80:81]
	v_pk_mul_f32 v[92:93], v[150:151], v[86:87] op_sel_hi:[1,0]
	v_pk_mul_f32 v[94:95], v[134:135], v[86:87] op_sel_hi:[1,0]
	v_pk_mul_f32 v[92:93], v[12:13], v[92:93]
	v_pk_mul_f32 v[94:95], v[14:15], v[94:95]
	global_store_dwordx4 v[96:97], v[92:95], off
	s_nop 1
	v_pk_mul_f32 v[92:93], v[148:149], v[86:87] op_sel_hi:[1,0]
	v_pk_mul_f32 v[94:95], v[132:133], v[86:87] op_sel_hi:[1,0]
	v_pk_mul_f32 v[92:93], v[8:9], v[92:93]
	v_pk_mul_f32 v[94:95], v[10:11], v[94:95]
	global_store_dwordx4 v[96:97], v[92:95], off offset:16
	s_nop 1
	v_pk_mul_f32 v[92:93], v[164:165], v[86:87] op_sel_hi:[1,0]
	v_pk_mul_f32 v[94:95], v[130:131], v[86:87] op_sel_hi:[1,0]
	v_pk_mul_f32 v[92:93], v[4:5], v[92:93]
	v_pk_mul_f32 v[94:95], v[6:7], v[94:95]
	global_store_dwordx4 v[96:97], v[92:95], off offset:512
	s_nop 1
	v_pk_mul_f32 v[92:93], v[166:167], v[86:87] op_sel_hi:[1,0]
	v_pk_mul_f32 v[86:87], v[162:163], v[86:87] op_sel_hi:[1,0]
	v_pk_mul_f32 v[92:93], v[0:1], v[92:93]
	v_pk_mul_f32 v[94:95], v[2:3], v[86:87]
	s_waitcnt vmcnt(17)
	v_pk_fma_f32 v[86:87], v[170:171], s[4:5], v[82:83] op_sel_hi:[1,0,0]
	global_store_dwordx4 v[96:97], v[92:95], off offset:528
	v_cmp_gt_f32_e32 vcc, s5, v87
	s_nop 0
	v_mul_f32_e32 v92, 0x4b800000, v87
	v_cndmask_b32_e32 v87, v87, v92, vcc
	v_rsq_f32_e32 v87, v87
	v_lshlrev_b64 v[92:93], 12, v[168:169]
	v_lshl_add_u64 v[92:93], s[70:71], 0, v[92:93]
	v_lshl_add_u64 v[92:93], v[92:93], 0, v[80:81]
	v_mul_f32_e32 v94, 0x45800000, v87
	v_cndmask_b32_e32 v94, v87, v94, vcc
	v_pk_mul_f32 v[52:53], v[52:53], v[94:95] op_sel_hi:[1,0]
	v_pk_mul_f32 v[54:55], v[54:55], v[94:95] op_sel_hi:[1,0]
	v_pk_mul_f32 v[52:53], v[4:5], v[52:53]
	v_pk_mul_f32 v[54:55], v[6:7], v[54:55]
	global_store_dwordx4 v[92:93], v[52:55], off offset:512
	v_cmp_gt_f32_e32 vcc, s5, v86
	v_pk_mul_f32 v[48:49], v[48:49], v[94:95] op_sel_hi:[1,0]
	v_mul_f32_e32 v52, 0x4b800000, v86
	v_cndmask_b32_e32 v52, v86, v52, vcc
	v_rsq_f32_e32 v52, v52
	v_pk_mul_f32 v[50:51], v[50:51], v[94:95] op_sel_hi:[1,0]
	v_pk_mul_f32 v[48:49], v[0:1], v[48:49]
	v_pk_mul_f32 v[50:51], v[2:3], v[50:51]
	global_store_dwordx4 v[92:93], v[48:51], off offset:528
	v_pk_mul_f32 v[62:63], v[62:63], v[94:95] op_sel_hi:[1,0]
	v_pk_mul_f32 v[60:61], v[60:61], v[94:95] op_sel_hi:[1,0]
	v_mul_f32_e32 v48, 0x45800000, v52
	v_cndmask_b32_e32 v48, v52, v48, vcc
	v_lshlrev_b64 v[50:51], 12, v[128:129]
	v_lshl_add_u64 v[50:51], s[70:71], 0, v[50:51]
	v_pk_mul_f32 v[36:37], v[36:37], v[48:49] op_sel_hi:[1,0]
	v_pk_mul_f32 v[38:39], v[38:39], v[48:49] op_sel_hi:[1,0]
	v_lshl_add_u64 v[50:51], v[50:51], 0, v[80:81]
	v_pk_mul_f32 v[38:39], v[6:7], v[38:39]
	v_pk_mul_f32 v[36:37], v[4:5], v[36:37]
	v_pk_mul_f32 v[28:29], v[28:29], v[48:49] op_sel_hi:[1,0]
	v_pk_mul_f32 v[30:31], v[30:31], v[48:49] op_sel_hi:[1,0]
	global_store_dwordx4 v[50:51], v[36:39], off offset:512
	v_pk_mul_f32 v[30:31], v[2:3], v[30:31]
	v_pk_mul_f32 v[28:29], v[0:1], v[28:29]
	s_waitcnt vmcnt(19)
	v_pk_fma_f32 v[36:37], v[84:85], s[4:5], v[82:83] op_sel_hi:[1,0,0]
	global_store_dwordx4 v[50:51], v[28:31], off offset:528
	v_cmp_gt_f32_e32 vcc, s5, v37
	v_pk_mul_f32 v[40:41], v[40:41], v[48:49] op_sel_hi:[1,0]
	v_mul_f32_e32 v28, 0x4b800000, v37
	v_cndmask_b32_e32 v28, v37, v28, vcc
	v_rsq_f32_e32 v30, v28
	v_lshlrev_b64 v[28:29], 12, v[90:91]
	v_pk_mul_f32 v[42:43], v[42:43], v[48:49] op_sel_hi:[1,0]
	v_lshl_add_u64 v[28:29], s[70:71], 0, v[28:29]
	v_pk_mul_f32 v[42:43], v[10:11], v[42:43]
	v_pk_mul_f32 v[40:41], v[8:9], v[40:41]
	v_lshl_add_u64 v[38:39], v[28:29], 0, v[80:81]
	v_mul_f32_e32 v28, 0x45800000, v30
	global_store_dwordx4 v[50:51], v[40:43], off offset:16
	v_pk_mul_f32 v[46:47], v[46:47], v[48:49] op_sel_hi:[1,0]
	v_pk_mul_f32 v[62:63], v[14:15], v[62:63]
	v_cndmask_b32_e32 v40, v30, v28, vcc
	v_pk_mul_f32 v[24:25], v[24:25], v[40:41] op_sel_hi:[1,0]
	v_pk_mul_f32 v[26:27], v[26:27], v[40:41] op_sel_hi:[1,0]
	v_pk_mul_f32 v[24:25], v[8:9], v[24:25]
	v_pk_mul_f32 v[26:27], v[10:11], v[26:27]
	global_store_dwordx4 v[38:39], v[24:27], off offset:16
	v_pk_mul_f32 v[22:23], v[22:23], v[40:41] op_sel_hi:[1,0]
	v_cmp_gt_f32_e32 vcc, s5, v36
	v_pk_mul_f32 v[26:27], v[72:73], v[40:41] op_sel_hi:[1,0]
	v_pk_mul_f32 v[24:25], v[6:7], v[22:23]
	v_pk_mul_f32 v[22:23], v[4:5], v[26:27]
	global_store_dwordx4 v[38:39], v[22:25], off offset:512
	v_pk_mul_f32 v[20:21], v[20:21], v[40:41] op_sel_hi:[1,0]
	v_pk_mul_f32 v[30:31], v[34:35], v[40:41] op_sel_hi:[1,0]
	v_mul_f32_e32 v22, 0x4b800000, v36
	v_cndmask_b32_e32 v22, v36, v22, vcc
	v_rsq_f32_e32 v26, v22
	v_pk_mul_f32 v[24:25], v[74:75], v[40:41] op_sel_hi:[1,0]
	v_pk_mul_f32 v[22:23], v[2:3], v[20:21]
	v_pk_mul_f32 v[20:21], v[0:1], v[24:25]
	global_store_dwordx4 v[38:39], v[20:23], off offset:528
	v_pk_mul_f32 v[44:45], v[44:45], v[48:49] op_sel_hi:[1,0]
	v_pk_mul_f32 v[46:47], v[14:15], v[46:47]
	v_mul_f32_e32 v20, 0x45800000, v26
	v_cndmask_b32_e32 v20, v26, v20, vcc
	v_lshlrev_b64 v[22:23], 12, v[88:89]
	v_pk_mul_f32 v[18:19], v[18:19], v[20:21] op_sel_hi:[1,0]
	v_pk_mul_f32 v[28:29], v[32:33], v[40:41] op_sel_hi:[1,0]
	v_pk_mul_f32 v[30:31], v[14:15], v[30:31]
	v_pk_mul_f32 v[24:25], v[70:71], v[20:21] op_sel_hi:[1,0]
	v_pk_mul_f32 v[14:15], v[14:15], v[18:19]
	v_lshl_add_u64 v[18:19], s[70:71], 0, v[22:23]
	v_pk_mul_f32 v[60:61], v[12:13], v[60:61]
	v_pk_mul_f32 v[44:45], v[12:13], v[44:45]
	v_pk_mul_f32 v[28:29], v[12:13], v[28:29]
	v_pk_mul_f32 v[12:13], v[12:13], v[24:25]
	v_lshl_add_u64 v[18:19], v[18:19], 0, v[80:81]
	v_pk_mul_f32 v[56:57], v[56:57], v[94:95] op_sel_hi:[1,0]
	v_pk_mul_f32 v[58:59], v[58:59], v[94:95] op_sel_hi:[1,0]
	global_store_dwordx4 v[18:19], v[12:15], off
	v_pk_mul_f32 v[58:59], v[10:11], v[58:59]
	v_pk_mul_f32 v[56:57], v[8:9], v[56:57]
	v_pk_mul_f32 v[12:13], v[68:69], v[20:21] op_sel_hi:[1,0]
	v_pk_mul_f32 v[14:15], v[16:17], v[20:21] op_sel_hi:[1,0]
	v_pk_mul_f32 v[8:9], v[8:9], v[12:13]
	v_pk_mul_f32 v[10:11], v[10:11], v[14:15]
	global_store_dwordx4 v[18:19], v[8:11], off offset:16
	global_store_dwordx4 v[92:93], v[60:63], off
	global_store_dwordx4 v[92:93], v[56:59], off offset:16
	v_pk_mul_f32 v[8:9], v[76:77], v[20:21] op_sel_hi:[1,0]
	v_pk_mul_f32 v[10:11], v[64:65], v[20:21] op_sel_hi:[1,0]
	v_pk_mul_f32 v[4:5], v[4:5], v[8:9]
	v_pk_mul_f32 v[6:7], v[6:7], v[10:11]
	global_store_dwordx4 v[18:19], v[4:7], off offset:512
	global_store_dwordx4 v[50:51], v[44:47], off
	global_store_dwordx4 v[38:39], v[28:31], off
	v_pk_mul_f32 v[4:5], v[78:79], v[20:21] op_sel_hi:[1,0]
	v_pk_mul_f32 v[6:7], v[66:67], v[20:21] op_sel_hi:[1,0]
	v_pk_mul_f32 v[0:1], v[0:1], v[4:5]
	v_pk_mul_f32 v[2:3], v[2:3], v[6:7]
	global_store_dwordx4 v[18:19], v[0:3], off offset:528
	s_endpgm
